# v24: v22 plus fallbacks - pinning and relocated table build only when gridDim>=512, else baseline paths
# speedup vs baseline: 1.0477x; 1.0020x over previous
.LBB0_17:
	s_or_b64 exec, exec, s[4:5]
	s_load_dword s33, s[0:1], 0x290
	v_lshl_add_u32 v104, s2, 8, v100
	v_and_b32_e32 v96, 63, v100
	v_and_b32_e32 v101, 31, v100
	v_ashrrev_i32_e32 v70, 6, v104
	s_movk_i32 s0, 0x4000
	s_waitcnt lgkmcnt(0)
	s_lshl_b32 s24, s33, 2
	v_cmp_gt_i32_e32 vcc, s0, v70
	v_lshrrev_b32_e32 v107, 5, v96
	v_lshlrev_b32_e32 v102, 2, v101
	v_mbcnt_lo_u32_b32 v139, -1, 0
	v_lshlrev_b32_e32 v98, 4, v101
	s_cmp_lt_u32 s33, 0x200
	s_cbranch_scc1 .Lmy_tq_orig
	s_mov_b64 s[16:17], exec
	s_branch .LBB0_22
.Lmy_tq_orig:
	s_and_saveexec_b64 s[16:17], vcc
	s_cbranch_execz .LBB0_22
	v_mbcnt_hi_u32_b32 v0, -1, v139
	v_and_b32_e32 v1, 64, v0
	v_add_u32_e32 v1, 64, v1
	v_xor_b32_e32 v2, 16, v0
	v_cmp_lt_i32_e32 vcc, v2, v1
	v_readlane_b32 s36, v238, 0
	v_readlane_b32 s37, v238, 1
	v_cndmask_b32_e32 v2, v0, v2, vcc
	v_lshlrev_b32_e32 v71, 2, v2
	v_xor_b32_e32 v2, 8, v0
	v_cmp_lt_i32_e32 vcc, v2, v1
	v_readlane_b32 s38, v238, 2
	v_readlane_b32 s39, v238, 3
	v_cndmask_b32_e32 v2, v0, v2, vcc
	v_lshlrev_b32_e32 v72, 2, v2
	v_xor_b32_e32 v2, 4, v0
	v_cmp_lt_i32_e32 vcc, v2, v1
	v_readlane_b32 s40, v238, 4
	v_readlane_b32 s41, v238, 5
	v_cndmask_b32_e32 v2, v0, v2, vcc
	v_lshlrev_b32_e32 v73, 2, v2
	v_xor_b32_e32 v2, 2, v0
	v_cmp_lt_i32_e32 vcc, v2, v1
	v_readlane_b32 s42, v238, 6
	v_readlane_b32 s43, v238, 7
	v_cndmask_b32_e32 v2, v0, v2, vcc
	v_lshlrev_b32_e32 v74, 2, v2
	v_xor_b32_e32 v2, 1, v0
	v_readlane_b32 s44, v238, 8
	v_readlane_b32 s45, v238, 9
	v_readlane_b32 s46, v238, 10
	v_readlane_b32 s47, v238, 11
	v_readlane_b32 s48, v238, 12
	v_readlane_b32 s49, v238, 13
	v_readlane_b32 s50, v238, 14
	v_readlane_b32 s51, v238, 15
	v_cmp_lt_i32_e32 vcc, v2, v1
	v_mov_b32_e32 v77, s49
	v_mov_b32_e32 v78, s51
	v_mov_b32_e32 v79, s48
	v_mov_b32_e32 v80, s50
	v_readlane_b32 s36, v238, 16
	v_mov_b32_e32 v33, 0
	v_cndmask_b32_e32 v0, v0, v2, vcc
	v_readlane_b32 s40, v238, 20
	v_readlane_b32 s41, v238, 21
	v_readlane_b32 s42, v238, 22
	v_readlane_b32 s43, v238, 23
	v_mov_b32_e32 v99, v33
	v_cmp_eq_u32_e64 s[0:1], 0, v101
	v_lshlrev_b32_e32 v75, 2, v0
	v_lshl_or_b32 v76, v70, 1, v107
	s_lshl_b32 s12, s33, 3
	s_mov_b64 s[10:11], 0
	s_movk_i32 s13, 0x3fff
	v_lshlrev_b32_e32 v34, 2, v102
	v_mov_b32_e32 v35, v33
	v_mov_b32_e32 v81, s41
	v_mov_b32_e32 v82, s43
	v_mov_b32_e32 v83, s40
	v_mov_b32_e32 v84, s42
	s_mov_b32 s94, 0x40c00000
	s_mov_b32 s95, 0x3e800000
	s_mov_b32 s96, 0x3f400000
	s_mov_b32 s97, 0x3fa00000
	s_mov_b32 s14, 0x3fe00000
	s_mov_b32 s15, 0x40600000
	s_mov_b32 s3, 0x40200000
	s_mov_b32 s8, 0x40a00000
	v_readlane_b32 s37, v238, 17
	v_readlane_b32 s38, v238, 18
	v_readlane_b32 s39, v238, 19
	v_readlane_b32 s44, v238, 24
	v_readlane_b32 s45, v238, 25
	v_readlane_b32 s46, v238, 26
	v_readlane_b32 s47, v238, 27
	v_readlane_b32 s48, v238, 28
	v_readlane_b32 s49, v238, 29
	v_readlane_b32 s50, v238, 30
	v_readlane_b32 s51, v238, 31
	s_branch .LBB0_20

.LBB0_450:
	s_barrier
	s_mov_b64 s[8:9], exec
	v_readlane_b32 s10, v237, 0
	v_readlane_b32 s11, v237, 1
	s_and_b64 s[10:11], s[8:9], s[10:11]
	s_mov_b64 exec, s[10:11]
	s_cbranch_execz .LBB0_454
	s_mov_b64 s[12:13], exec
	v_mbcnt_lo_u32_b32 v0, s12, 0
	v_mbcnt_hi_u32_b32 v0, s13, v0
	v_cmp_eq_u32_e32 vcc, 0, v0
	s_and_saveexec_b64 s[10:11], vcc
	s_cbranch_execz .LBB0_453
	s_bcnt1_i32_b64 s3, s[12:13]
	v_mov_b32_e32 v1, s3
	s_cmp_lt_u32 s33, 0x200
	s_cbranch_scc1 .Lmy_pin_atomic
	s_cmp_eq_u32 s98, 0
	s_cselect_b32 s3, s2, 0x1000
	s_mov_b32 s98, 1
	v_mov_b32_e32 v1, s3
	s_branch .Lmy_pin_join
.Lmy_pin_atomic:
	global_atomic_add v1, v49, v1, s[92:93] sc0
.Lmy_pin_join:
.LBB0_453:
	s_or_b64 exec, exec, s[10:11]
	s_mov_b64 s[10:11], src_shared_base
	s_waitcnt vmcnt(0)
	v_readfirstlane_b32 s3, v1
	v_mov_b32_e32 v53, s11
	s_nop 0
	v_add_u32_e32 v0, s3, v0
	flat_store_dword v[52:53], v0 sc0 sc1
	s_waitcnt vmcnt(0)

.LBB0_583:
	s_or_b64 exec, exec, s[60:61]
	s_waitcnt vmcnt(0)
	s_cmp_lt_u32 s33, 0x200
	s_cbranch_scc1 .Lmy_tq_skip
	s_cmp_lt_u32 s2, 0x100
	s_cbranch_scc1 .Lmy_tq_skip
	v_ashrrev_i32_e32 v70, 6, v104
	v_subrev_u32_e32 v70, 0x400, v70
	s_sub_u32 s24, s33, 0x100
	s_lshl_b32 s24, s24, 2
	v_mbcnt_lo_u32_b32 v255, -1, 0
	v_mov_b32_e32 v242, v98
	v_mov_b32_e32 v244, v102
	s_mov_b64 s[22:23], exec
	v_mbcnt_hi_u32_b32 v0, -1, v255
	v_and_b32_e32 v1, 64, v0
	v_add_u32_e32 v1, 64, v1
	v_xor_b32_e32 v2, 16, v0
	v_cmp_lt_i32_e32 vcc, v2, v1
	v_readlane_b32 s36, v238, 0
	v_readlane_b32 s37, v238, 1
	v_cndmask_b32_e32 v2, v0, v2, vcc
	v_lshlrev_b32_e32 v71, 2, v2
	v_xor_b32_e32 v2, 8, v0
	v_cmp_lt_i32_e32 vcc, v2, v1
	v_readlane_b32 s38, v238, 2
	v_readlane_b32 s39, v238, 3
	v_cndmask_b32_e32 v2, v0, v2, vcc
	v_lshlrev_b32_e32 v72, 2, v2
	v_xor_b32_e32 v2, 4, v0
	v_cmp_lt_i32_e32 vcc, v2, v1
	v_readlane_b32 s40, v238, 4
	v_readlane_b32 s41, v238, 5
	v_cndmask_b32_e32 v2, v0, v2, vcc
	v_lshlrev_b32_e32 v73, 2, v2
	v_xor_b32_e32 v2, 2, v0
	v_cmp_lt_i32_e32 vcc, v2, v1
	v_readlane_b32 s42, v238, 6
	v_readlane_b32 s43, v238, 7
	v_cndmask_b32_e32 v2, v0, v2, vcc
	v_lshlrev_b32_e32 v74, 2, v2
	v_xor_b32_e32 v2, 1, v0
	v_readlane_b32 s44, v238, 8
	v_readlane_b32 s45, v238, 9
	v_readlane_b32 s46, v238, 10
	v_readlane_b32 s47, v238, 11
	v_readlane_b32 s48, v238, 12
	v_readlane_b32 s49, v238, 13
	v_readlane_b32 s50, v238, 14
	v_readlane_b32 s51, v238, 15
	v_cmp_lt_i32_e32 vcc, v2, v1
	v_mov_b32_e32 v77, s49
	v_mov_b32_e32 v78, s51
	v_mov_b32_e32 v79, s48
	v_mov_b32_e32 v80, s50
	v_readlane_b32 s36, v238, 16
	v_mov_b32_e32 v247, 0
	v_cndmask_b32_e32 v0, v0, v2, vcc
	v_readlane_b32 s40, v238, 20
	v_readlane_b32 s41, v238, 21
	v_readlane_b32 s42, v238, 22
	v_readlane_b32 s43, v238, 23
	v_mov_b32_e32 v243, v247
	v_cmp_eq_u32_e64 s[0:1], 0, v101
	v_lshlrev_b32_e32 v75, 2, v0
	v_lshl_or_b32 v76, v70, 1, v107
	s_lshl_b32 s12, s24, 1
	s_mov_b64 s[10:11], 0
	s_movk_i32 s13, 0x3fff
	v_lshlrev_b32_e32 v34, 2, v244
	v_mov_b32_e32 v35, v247
	v_mov_b32_e32 v81, s41
	v_mov_b32_e32 v82, s43
	v_mov_b32_e32 v83, s40
	v_mov_b32_e32 v84, s42
	s_mov_b32 s94, 0x40c00000
	s_mov_b32 s95, 0x3e800000
	s_mov_b32 s96, 0x3f400000
	s_mov_b32 s97, 0x3fa00000
	s_mov_b32 s14, 0x3fe00000
	s_mov_b32 s15, 0x40600000
	s_mov_b32 s3, 0x40200000
	s_mov_b32 s20, 0x40a00000
	v_readlane_b32 s37, v238, 17
	v_readlane_b32 s38, v238, 18
	v_readlane_b32 s39, v238, 19
	v_readlane_b32 s44, v238, 24
	v_readlane_b32 s45, v238, 25
	v_readlane_b32 s46, v238, 26
	v_readlane_b32 s47, v238, 27
	v_readlane_b32 s48, v238, 28
	v_readlane_b32 s49, v238, 29
	v_readlane_b32 s50, v238, 30
	v_readlane_b32 s51, v238, 31
	s_branch .Lmy_tq_20
